# P1: per-row rstd loads of the epilogue hoisted to the top of each unit's K-loop (free registers)
# baseline (speedup 1.0000x reference)
; template <class Epi, class Sched, bool ALIGN_EPI = false, bool SP2 = false>
; __device__ __forceinline__ void gemm_phase(PG8_LAS unsigned char* lds, const Gemm g, const Sched& S, const Epi& E) {
;     ...
;     f32x4 acc[2][2][4][2];
; #pragma unroll
;     for (int a = 0; a < 2; ++a)
; #pragma unroll
;         for (int b = 0; b < 2; ++b)
; #pragma unroll
;             for (int m = 0; m < 4; ++m)
; #pragma unroll
;                 for (int n = 0; n < 2; ++n) acc[a][b][m][n] = (f32x4){0.f, 0.f, 0.f, 0.f};
;     __device__ __forceinline__ void operator()(const f32x4 (&acc)[2][2][4][2], const Unit& u, int wr, int wc, int fr, int fq) const {
;     ...
;         if (layer == 0) {
; #pragma unroll
;             for (int ai = 0; ai < 2; ++ai)
; #pragma unroll
;                 for (int m = 0; m < 4; ++m) rsv[ai][m] = rstd0[rowbase + ai * 128 + m * 16];
.LBB0_386:
	s_ashr_i32 s77, s76, 31
	s_lshl_b64 s[44:45], s[76:77], 19
	s_add_u32 s78, s26, s44
	s_addc_u32 s79, s27, s45
	s_and_b64 s[44:45], s[4:5], exec
	s_cselect_b32 s2, s79, s83
	s_cselect_b32 s7, s78, s82
	s_ashr_i32 s75, s74, 31
	s_lshl_b64 s[44:45], s[74:75], 19
	s_add_u32 s80, s50, s44
	s_addc_u32 s81, s51, s45
	s_and_b64 s[44:45], s[4:5], exec
	s_cselect_b32 s12, s81, s85
	s_cselect_b32 s17, s80, s84
	s_add_u32 s82, s82, 0x40080
	.p2align 6
	s_addc_u32 s83, s83, 0
	s_add_u32 s44, s84, 0x100
	v_mov_b32_e32 v0, 0
	s_addc_u32 s45, s85, 0
	s_mov_b32 s75, -2
	v_mov_b32_e32 v1, v0
	s_waitcnt lgkmcnt(0)
	v_mov_b32_e32 v2, v0
	v_mov_b32_e32 v3, v0
	v_mov_b32_e32 v8, v0
	v_mov_b32_e32 v9, v0
	v_mov_b32_e32 v10, v0
	v_mov_b32_e32 v11, v0
	v_mov_b32_e32 v16, v0
	v_mov_b32_e32 v17, v0
	v_mov_b32_e32 v18, v0
	v_mov_b32_e32 v19, v0
	v_mov_b32_e32 v24, v0
	v_mov_b32_e32 v25, v0
	v_mov_b32_e32 v26, v0
	v_mov_b32_e32 v27, v0
	v_mov_b32_e32 v32, v0
	v_mov_b32_e32 v33, v0
	v_mov_b32_e32 v34, v0
	v_mov_b32_e32 v35, v0
	v_mov_b32_e32 v40, v0
	v_mov_b32_e32 v41, v0
	v_mov_b32_e32 v42, v0
	v_mov_b32_e32 v43, v0
	v_mov_b32_e32 v48, v0
	v_mov_b32_e32 v49, v0
	v_mov_b32_e32 v50, v0
	v_mov_b32_e32 v51, v0
	v_mov_b32_e32 v56, v0
	v_mov_b32_e32 v57, v0
	v_mov_b32_e32 v58, v0
	v_mov_b32_e32 v59, v0
	v_mov_b32_e32 v4, v0
	v_mov_b32_e32 v5, v0
	v_mov_b32_e32 v6, v0
	v_mov_b32_e32 v7, v0
	v_mov_b32_e32 v12, v0
	v_mov_b32_e32 v13, v0
	v_mov_b32_e32 v14, v0
	v_mov_b32_e32 v15, v0
	v_mov_b32_e32 v20, v0
	v_mov_b32_e32 v21, v0
	v_mov_b32_e32 v22, v0
	v_mov_b32_e32 v23, v0
	v_mov_b32_e32 v28, v0
	v_mov_b32_e32 v29, v0
	v_mov_b32_e32 v30, v0
	v_mov_b32_e32 v31, v0
	v_mov_b32_e32 v36, v0
	v_mov_b32_e32 v37, v0
	v_mov_b32_e32 v38, v0
	v_mov_b32_e32 v39, v0
	v_mov_b32_e32 v44, v0
	v_mov_b32_e32 v45, v0
	v_mov_b32_e32 v46, v0
	v_mov_b32_e32 v47, v0
	v_mov_b32_e32 v52, v0
	v_mov_b32_e32 v53, v0
	v_mov_b32_e32 v54, v0
	v_mov_b32_e32 v55, v0
	v_mov_b32_e32 v60, v0
	v_mov_b32_e32 v61, v0
	v_mov_b32_e32 v62, v0
	v_mov_b32_e32 v63, v0
	v_mov_b32_e32 v64, v0
	v_mov_b32_e32 v65, v0
	v_mov_b32_e32 v66, v0
	v_mov_b32_e32 v67, v0
	v_mov_b32_e32 v72, v0
	v_mov_b32_e32 v73, v0
	v_mov_b32_e32 v74, v0
	v_mov_b32_e32 v75, v0
	v_mov_b32_e32 v80, v0
	v_mov_b32_e32 v81, v0
	v_mov_b32_e32 v82, v0
	v_mov_b32_e32 v83, v0
	v_mov_b32_e32 v88, v0
	v_mov_b32_e32 v89, v0
	v_mov_b32_e32 v90, v0
	v_mov_b32_e32 v91, v0
	v_mov_b32_e32 v96, v0
	v_mov_b32_e32 v97, v0
	v_mov_b32_e32 v98, v0
	v_mov_b32_e32 v99, v0
	v_mov_b32_e32 v104, v0
	v_mov_b32_e32 v105, v0
	v_mov_b32_e32 v106, v0
	v_mov_b32_e32 v107, v0
	v_mov_b32_e32 v112, v0
	v_mov_b32_e32 v113, v0
	v_mov_b32_e32 v114, v0
	v_mov_b32_e32 v115, v0
	v_mov_b32_e32 v120, v0
	v_mov_b32_e32 v121, v0
	v_mov_b32_e32 v122, v0
	v_mov_b32_e32 v123, v0
	v_mov_b32_e32 v68, v0
	v_mov_b32_e32 v69, v0
	v_mov_b32_e32 v70, v0
	v_mov_b32_e32 v71, v0
	v_mov_b32_e32 v76, v0
	v_mov_b32_e32 v77, v0
	v_mov_b32_e32 v78, v0
	v_mov_b32_e32 v79, v0
	v_mov_b32_e32 v84, v0
	v_mov_b32_e32 v85, v0
	v_mov_b32_e32 v86, v0
	v_mov_b32_e32 v87, v0
	v_mov_b32_e32 v92, v0
	v_mov_b32_e32 v93, v0
	v_mov_b32_e32 v94, v0
	v_mov_b32_e32 v95, v0
	v_mov_b32_e32 v100, v0
	v_mov_b32_e32 v101, v0
	v_mov_b32_e32 v102, v0
	v_mov_b32_e32 v103, v0
	v_mov_b32_e32 v108, v0
	v_mov_b32_e32 v109, v0
	v_mov_b32_e32 v110, v0
	v_mov_b32_e32 v111, v0
	v_mov_b32_e32 v116, v0
	v_mov_b32_e32 v117, v0
	v_mov_b32_e32 v118, v0
	v_mov_b32_e32 v119, v0
	v_mov_b32_e32 v124, v0
	v_mov_b32_e32 v125, v0
	v_mov_b32_e32 v126, v0
	v_mov_b32_e32 v127, v0
	s_lshl_b32 vcc_lo, s10, 8
	v_add_u32_e32 v132, vcc_lo, v151
	v_ashrrev_i32_e32 v133, 31, v132
	v_lshl_add_u64 v[130:131], v[132:133], 2, s[8:9]
	global_load_dword v225, v[130:131], off
	global_load_dword v235, v[130:131], off offset:64
	global_load_dword v180, v[130:131], off offset:128
	global_load_dword v176, v[130:131], off offset:192
	global_load_dword v174, v[130:131], off offset:512
	global_load_dword v172, v[130:131], off offset:576
	global_load_dword v170, v[130:131], off offset:640
	global_load_dword v166, v[130:131], off offset:704

; DI unsigned cvt_pk(float lo, float hi) { const f32x2 v = {lo, hi}; return __builtin_bit_cast(unsigned, __builtin_convertvector(v, bf16v2)); }
;     __device__ __forceinline__ void operator()(const f32x4 (&acc)[2][2][4][2], const Unit& u, int wr, int wc, int fr, int fq) const {
;     ...
;                 for (int m = 0; m < 4; ++m) rsv[ai][m] = rstd0[rowbase + ai * 128 + m * 16];
;     ...
;         } else {
; #pragma unroll
;             for (int ai = 0; ai < 2; ++ai)
; #pragma unroll
;                 for (int m = 0; m < 4; ++m) {
;                     const int row = rowbase + ai * 128 + m * 16; const float r = ROW_RS(ai, m);
; #pragma unroll
;                     for (int bj = 0; bj < 2; ++bj) {
;                         float sv[8];
; #pragma unroll
;                         for (int n = 0; n < 2; ++n)
; #pragma unroll
;                             for (int j = 0; j < 4; ++j) { const float z = acc[ai][bj][m][n][j] * r; sv[4 * n + j] = z * __builtin_amdgcn_rcpf(1.0f + __builtin_amdgcn_exp2f(-1.44269504088896341f * z)); }
;                         u32x4 w; w.x = cvt_pk(sv[0], sv[1]); w.y = cvt_pk(sv[2], sv[3]); w.z = cvt_pk(sv[4], sv[5]); w.w = cvt_pk(sv[6], sv[7]);
;                         *(u32x4*)(zs + (size_t)row * DM + zcol + 32 * bj + 8 * fq) = w;
;                     }
.LBB0_416:
	s_lshl_b32 s45, s10, 8
	v_add_u32_e32 v132, s45, v151
	v_ashrrev_i32_e32 v133, 31, v132
	v_lshl_add_u64 v[130:131], v[132:133], 2, s[8:9]
	v_mov_b32_e32 v128, v225
	v_mov_b32_e32 v200, v235
	s_ashr_i32 s44, s10, 4
	s_and_b32 s45, s45, 0xf00
	v_add_u32_e32 v168, s45, v151
	s_ashr_i32 s45, s44, 31
	s_lshl_b64 s[82:83], s[44:45], 3
	s_or_b32 s82, s82, s2
	s_cmp_lt_i32 s17, 1
	s_mov_b64 s[90:91], -1
	s_cbranch_scc1 .LBB0_422
	s_cmp_lg_u32 s17, 1
	s_cbranch_scc0 .LBB0_419
	s_waitcnt vmcnt(0)
	v_pk_mul_f32 v[136:137], v[124:125], v[128:129] op_sel_hi:[1,0]
	v_lshl_add_u64 v[134:135], s[12:13], 1, v[156:157]
	v_mul_f32_e32 v129, 0xbfb8aa3b, v136
	v_exp_f32_e32 v129, v129
	v_lshlrev_b64 v[130:131], 11, v[132:133]
	v_lshl_add_u64 v[130:131], v[134:135], 0, v[130:131]
	s_mov_b32 s2, 0x40000
	v_add_f32_e32 v129, 1.0, v129
	v_rcp_f32_e32 v138, v129
	v_mul_f32_e32 v129, 0xbfb8aa3b, v137
	v_exp_f32_e32 v129, v129
	s_mov_b64 s[44:45], 0x40000
	s_mov_b64 s[90:91], 0
	v_add_f32_e32 v129, 1.0, v129
	v_rcp_f32_e32 v139, v129
	s_nop 0
	v_pk_mul_f32 v[136:137], v[136:137], v[138:139]
	v_pk_mul_f32 v[138:139], v[126:127], v[128:129] op_sel_hi:[1,0]
	v_cvt_pk_bf16_f32 v136, v136, v137
	v_mul_f32_e32 v129, 0xbfb8aa3b, v138
	v_exp_f32_e32 v129, v129
	s_nop 0
	v_add_f32_e32 v129, 1.0, v129
	v_rcp_f32_e32 v178, v129
	v_mul_f32_e32 v129, 0xbfb8aa3b, v139
	v_exp_f32_e32 v129, v129
	s_nop 0
	v_add_f32_e32 v129, 1.0, v129
	v_rcp_f32_e32 v179, v129
	s_nop 0
	v_pk_mul_f32 v[138:139], v[138:139], v[178:179]
	v_pk_mul_f32 v[178:179], v[116:117], v[128:129] op_sel_hi:[1,0]
	v_cvt_pk_bf16_f32 v137, v138, v139
	v_mul_f32_e32 v129, 0xbfb8aa3b, v178
	v_exp_f32_e32 v129, v129
	s_nop 0
	v_add_f32_e32 v129, 1.0, v129
	v_rcp_f32_e32 v182, v129
	v_mul_f32_e32 v129, 0xbfb8aa3b, v179
	v_exp_f32_e32 v129, v129
	s_nop 0
	v_add_f32_e32 v129, 1.0, v129
	v_rcp_f32_e32 v183, v129
	s_nop 0
	v_pk_mul_f32 v[178:179], v[178:179], v[182:183]
	v_pk_mul_f32 v[182:183], v[118:119], v[128:129] op_sel_hi:[1,0]
	v_cvt_pk_bf16_f32 v138, v178, v179
	v_mul_f32_e32 v129, 0xbfb8aa3b, v182
	v_exp_f32_e32 v129, v129
	s_nop 0
	v_add_f32_e32 v129, 1.0, v129
	v_rcp_f32_e32 v184, v129
	v_mul_f32_e32 v129, 0xbfb8aa3b, v183
	v_exp_f32_e32 v129, v129
	s_nop 0
	v_add_f32_e32 v129, 1.0, v129
	v_rcp_f32_e32 v185, v129
	s_nop 0
	v_pk_mul_f32 v[182:183], v[182:183], v[184:185]
	s_nop 0
	v_cvt_pk_bf16_f32 v139, v182, v183
	global_store_dwordx4 v[130:131], v[136:139], off
	s_nop 1
	v_pk_mul_f32 v[136:137], v[120:121], v[128:129] op_sel_hi:[1,0]
	s_nop 0
	v_mul_f32_e32 v129, 0xbfb8aa3b, v136
	v_exp_f32_e32 v129, v129
	s_nop 0
	v_add_f32_e32 v129, 1.0, v129
	v_rcp_f32_e32 v138, v129
	v_mul_f32_e32 v129, 0xbfb8aa3b, v137
	v_exp_f32_e32 v129, v129
	s_nop 0
	v_add_f32_e32 v129, 1.0, v129
	v_rcp_f32_e32 v139, v129
	s_nop 0
	v_pk_mul_f32 v[136:137], v[136:137], v[138:139]
	v_pk_mul_f32 v[138:139], v[122:123], v[128:129] op_sel_hi:[1,0]
	v_cvt_pk_bf16_f32 v136, v136, v137
	v_mul_f32_e32 v129, 0xbfb8aa3b, v138
	v_exp_f32_e32 v129, v129
	s_nop 0
	v_add_f32_e32 v129, 1.0, v129
	v_rcp_f32_e32 v178, v129
	v_mul_f32_e32 v129, 0xbfb8aa3b, v139
	v_exp_f32_e32 v129, v129
	s_nop 0
	v_add_f32_e32 v129, 1.0, v129
	v_rcp_f32_e32 v179, v129
	s_nop 0
	v_pk_mul_f32 v[138:139], v[138:139], v[178:179]
	v_pk_mul_f32 v[178:179], v[112:113], v[128:129] op_sel_hi:[1,0]
	v_cvt_pk_bf16_f32 v137, v138, v139
	v_mul_f32_e32 v129, 0xbfb8aa3b, v178
	v_exp_f32_e32 v129, v129
	s_nop 0
	v_add_f32_e32 v129, 1.0, v129
	v_rcp_f32_e32 v182, v129
	v_mul_f32_e32 v129, 0xbfb8aa3b, v179
	v_exp_f32_e32 v129, v129
	s_nop 0
	v_add_f32_e32 v129, 1.0, v129
	v_rcp_f32_e32 v183, v129
	s_nop 0
	v_pk_mul_f32 v[178:179], v[178:179], v[182:183]
	v_pk_mul_f32 v[182:183], v[114:115], v[128:129] op_sel_hi:[1,0]
	v_cvt_pk_bf16_f32 v138, v178, v179
	v_mul_f32_e32 v129, 0xbfb8aa3b, v182
	v_exp_f32_e32 v129, v129
	s_nop 0
	v_add_f32_e32 v129, 1.0, v129
	v_rcp_f32_e32 v184, v129
	v_mul_f32_e32 v129, 0xbfb8aa3b, v183
	v_exp_f32_e32 v129, v129
	s_nop 0
	v_add_f32_e32 v129, 1.0, v129
	v_rcp_f32_e32 v185, v129
	s_nop 0
	v_pk_mul_f32 v[182:183], v[182:183], v[184:185]
	s_nop 0
	v_cvt_pk_bf16_f32 v139, v182, v183
	global_store_dwordx4 v[130:131], v[136:139], off offset:64
	s_nop 1
	v_pk_mul_f32 v[138:139], v[108:109], v[200:201] op_sel_hi:[1,0]
	v_or_b32_e32 v136, 16, v132
	v_mul_f32_e32 v129, 0xbfb8aa3b, v138
	v_exp_f32_e32 v129, v129
	v_ashrrev_i32_e32 v137, 31, v136
	v_lshlrev_b64 v[136:137], 11, v[136:137]
	v_lshl_add_u64 v[136:137], v[134:135], 0, v[136:137]
	v_add_f32_e32 v129, 1.0, v129
	v_rcp_f32_e32 v178, v129
	v_mul_f32_e32 v129, 0xbfb8aa3b, v139
	v_exp_f32_e32 v129, v129
	s_nop 0
	v_add_f32_e32 v129, 1.0, v129
	v_rcp_f32_e32 v179, v129
	s_nop 0
	v_pk_mul_f32 v[138:139], v[138:139], v[178:179]
	v_pk_mul_f32 v[178:179], v[110:111], v[200:201] op_sel_hi:[1,0]
	s_nop 0
	v_mul_f32_e32 v129, 0xbfb8aa3b, v178
	v_exp_f32_e32 v129, v129
	s_nop 0
	v_add_f32_e32 v129, 1.0, v129
	v_rcp_f32_e32 v182, v129
	v_mul_f32_e32 v129, 0xbfb8aa3b, v179
	v_exp_f32_e32 v129, v129
	s_nop 0
	v_add_f32_e32 v129, 1.0, v129
	v_rcp_f32_e32 v183, v129
	s_nop 0
	v_pk_mul_f32 v[178:179], v[178:179], v[182:183]
	v_pk_mul_f32 v[182:183], v[100:101], v[200:201] op_sel_hi:[1,0]
	s_nop 0
	v_mul_f32_e32 v129, 0xbfb8aa3b, v182
	v_exp_f32_e32 v129, v129
	s_nop 0
	v_add_f32_e32 v129, 1.0, v129
	v_rcp_f32_e32 v184, v129
	v_mul_f32_e32 v129, 0xbfb8aa3b, v183
	v_exp_f32_e32 v129, v129
	s_nop 0
	v_add_f32_e32 v129, 1.0, v129
	v_rcp_f32_e32 v185, v129
	s_nop 0
	v_pk_mul_f32 v[184:185], v[182:183], v[184:185]
	v_pk_mul_f32 v[182:183], v[102:103], v[200:201] op_sel_hi:[1,0]
	v_cvt_pk_bf16_f32 v184, v184, v185
; DI unsigned cvt_pk(float lo, float hi) { const f32x2 v = {lo, hi}; return __builtin_bit_cast(unsigned, __builtin_convertvector(v, bf16v2)); }
;     __device__ __forceinline__ void operator()(const f32x4 (&acc)[2][2][4][2], const Unit& u, int wr, int wc, int fr, int fq) const {
;     ...
;                 for (int m = 0; m < 4; ++m) {
;                     const int row = rowbase + ai * 128 + m * 16; const float r = ROW_RS(ai, m);
; #pragma unroll
;                     for (int bj = 0; bj < 2; ++bj) {
;                         float sv[8];
; #pragma unroll
;                         for (int n = 0; n < 2; ++n)
; #pragma unroll
;                             for (int j = 0; j < 4; ++j) { const float z = acc[ai][bj][m][n][j] * r; sv[4 * n + j] = z * __builtin_amdgcn_rcpf(1.0f + __builtin_amdgcn_exp2f(-1.44269504088896341f * z)); }
;                         u32x4 w; w.x = cvt_pk(sv[0], sv[1]); w.y = cvt_pk(sv[2], sv[3]); w.z = cvt_pk(sv[4], sv[5]); w.w = cvt_pk(sv[6], sv[7]);
;                         *(u32x4*)(zs + (size_t)row * DM + zcol + 32 * bj + 8 * fq) = w;
;                     }
	v_mul_f32_e32 v129, 0xbfb8aa3b, v182
	v_exp_f32_e32 v129, v129
	s_nop 0
	v_add_f32_e32 v129, 1.0, v129
	v_rcp_f32_e32 v186, v129
	v_mul_f32_e32 v129, 0xbfb8aa3b, v183
	v_exp_f32_e32 v129, v129
	s_nop 0
	v_add_f32_e32 v129, 1.0, v129
	v_rcp_f32_e32 v187, v129
	s_nop 0
	v_pk_mul_f32 v[186:187], v[182:183], v[186:187]
	v_cvt_pk_bf16_f32 v182, v138, v139
	v_pk_mul_f32 v[138:139], v[104:105], v[200:201] op_sel_hi:[1,0]
	v_cvt_pk_bf16_f32 v183, v178, v179
	v_mul_f32_e32 v129, 0xbfb8aa3b, v138
	v_exp_f32_e32 v129, v129
	v_cvt_pk_bf16_f32 v185, v186, v187
	global_store_dwordx4 v[136:137], v[182:185], off
	v_add_f32_e32 v129, 1.0, v129
	v_rcp_f32_e32 v178, v129
	v_mul_f32_e32 v129, 0xbfb8aa3b, v139
	v_exp_f32_e32 v129, v129
	s_nop 0
	v_add_f32_e32 v129, 1.0, v129
	v_rcp_f32_e32 v179, v129
	s_nop 0
	v_pk_mul_f32 v[138:139], v[138:139], v[178:179]
	v_pk_mul_f32 v[178:179], v[106:107], v[200:201] op_sel_hi:[1,0]
	s_nop 0
	v_mul_f32_e32 v129, 0xbfb8aa3b, v178
	v_exp_f32_e32 v129, v129
	s_nop 0
	v_add_f32_e32 v129, 1.0, v129
	v_rcp_f32_e32 v182, v129
	v_mul_f32_e32 v129, 0xbfb8aa3b, v179
	v_exp_f32_e32 v129, v129
	s_nop 0
	v_add_f32_e32 v129, 1.0, v129
	v_rcp_f32_e32 v183, v129
	s_nop 0
	v_pk_mul_f32 v[178:179], v[178:179], v[182:183]
	v_pk_mul_f32 v[182:183], v[96:97], v[200:201] op_sel_hi:[1,0]
	s_nop 0
	v_mul_f32_e32 v129, 0xbfb8aa3b, v182
	v_exp_f32_e32 v129, v129
	s_nop 0
	v_add_f32_e32 v129, 1.0, v129
	v_rcp_f32_e32 v184, v129
	v_mul_f32_e32 v129, 0xbfb8aa3b, v183
	v_exp_f32_e32 v129, v129
	s_nop 0
	v_add_f32_e32 v129, 1.0, v129
	v_rcp_f32_e32 v185, v129
	s_nop 0
	v_pk_mul_f32 v[184:185], v[182:183], v[184:185]
	v_pk_mul_f32 v[182:183], v[98:99], v[200:201] op_sel_hi:[1,0]
	v_cvt_pk_bf16_f32 v184, v184, v185
	v_mul_f32_e32 v129, 0xbfb8aa3b, v182
	v_exp_f32_e32 v129, v129
	s_nop 0
	v_add_f32_e32 v129, 1.0, v129
	v_rcp_f32_e32 v186, v129
	v_mul_f32_e32 v129, 0xbfb8aa3b, v183
	v_exp_f32_e32 v129, v129
	s_nop 0
	v_add_f32_e32 v129, 1.0, v129
	v_rcp_f32_e32 v187, v129
	s_nop 0
	v_pk_mul_f32 v[186:187], v[182:183], v[186:187]
	v_cvt_pk_bf16_f32 v182, v138, v139
	v_pk_mul_f32 v[138:139], v[92:93], v[180:181] op_sel_hi:[1,0]
	v_cvt_pk_bf16_f32 v183, v178, v179
	v_mul_f32_e32 v129, 0xbfb8aa3b, v138
	v_exp_f32_e32 v129, v129
	v_cvt_pk_bf16_f32 v185, v186, v187
	global_store_dwordx4 v[136:137], v[182:185], off offset:64
	v_or_b32_e32 v136, 32, v132
	v_add_f32_e32 v129, 1.0, v129
	v_rcp_f32_e32 v178, v129
	v_mul_f32_e32 v129, 0xbfb8aa3b, v139
	v_exp_f32_e32 v129, v129
	v_ashrrev_i32_e32 v137, 31, v136
	v_lshlrev_b64 v[136:137], 11, v[136:137]
	v_lshl_add_u64 v[136:137], v[134:135], 0, v[136:137]
	v_add_f32_e32 v129, 1.0, v129
	v_rcp_f32_e32 v179, v129
	v_or_b32_e32 v132, 48, v132
	v_ashrrev_i32_e32 v133, 31, v132
	v_lshlrev_b64 v[132:133], 11, v[132:133]
	v_pk_mul_f32 v[138:139], v[138:139], v[178:179]
	v_pk_mul_f32 v[178:179], v[94:95], v[180:181] op_sel_hi:[1,0]
	v_lshl_add_u64 v[132:133], v[134:135], 0, v[132:133]
	v_mul_f32_e32 v129, 0xbfb8aa3b, v178
	v_exp_f32_e32 v129, v129
	v_pk_mul_f32 v[134:135], v[76:77], v[176:177] op_sel_hi:[1,0]
	v_add_f32_e32 v129, 1.0, v129
	v_rcp_f32_e32 v182, v129
	v_mul_f32_e32 v129, 0xbfb8aa3b, v179
	v_exp_f32_e32 v129, v129
	s_nop 0
	v_add_f32_e32 v129, 1.0, v129
	v_rcp_f32_e32 v183, v129
	s_nop 0
	v_pk_mul_f32 v[178:179], v[178:179], v[182:183]
	v_pk_mul_f32 v[182:183], v[84:85], v[180:181] op_sel_hi:[1,0]
	s_nop 0
	v_mul_f32_e32 v129, 0xbfb8aa3b, v182
	v_exp_f32_e32 v129, v129
	s_nop 0
	v_add_f32_e32 v129, 1.0, v129
	v_rcp_f32_e32 v184, v129
	v_mul_f32_e32 v129, 0xbfb8aa3b, v183
	v_exp_f32_e32 v129, v129
	s_nop 0
	v_add_f32_e32 v129, 1.0, v129
	v_rcp_f32_e32 v185, v129
	s_nop 0
	v_pk_mul_f32 v[184:185], v[182:183], v[184:185]
	v_pk_mul_f32 v[182:183], v[86:87], v[180:181] op_sel_hi:[1,0]
	v_cvt_pk_bf16_f32 v184, v184, v185
	v_mul_f32_e32 v129, 0xbfb8aa3b, v182
	v_exp_f32_e32 v129, v129
	s_nop 0
	v_add_f32_e32 v129, 1.0, v129
	v_rcp_f32_e32 v186, v129
	v_mul_f32_e32 v129, 0xbfb8aa3b, v183
	v_exp_f32_e32 v129, v129
	s_nop 0
	v_add_f32_e32 v129, 1.0, v129
	v_rcp_f32_e32 v187, v129
	s_nop 0
	v_pk_mul_f32 v[186:187], v[182:183], v[186:187]
	v_cvt_pk_bf16_f32 v182, v138, v139
	v_pk_mul_f32 v[138:139], v[88:89], v[180:181] op_sel_hi:[1,0]
	v_cvt_pk_bf16_f32 v183, v178, v179
	v_mul_f32_e32 v129, 0xbfb8aa3b, v138
	v_exp_f32_e32 v129, v129
	v_cvt_pk_bf16_f32 v185, v186, v187
	global_store_dwordx4 v[136:137], v[182:185], off
	v_add_f32_e32 v129, 1.0, v129
	v_rcp_f32_e32 v178, v129
	v_mul_f32_e32 v129, 0xbfb8aa3b, v139
	v_exp_f32_e32 v129, v129
	s_nop 0
	v_add_f32_e32 v129, 1.0, v129
	v_rcp_f32_e32 v179, v129
	s_nop 0
	v_pk_mul_f32 v[138:139], v[138:139], v[178:179]
	v_pk_mul_f32 v[178:179], v[90:91], v[180:181] op_sel_hi:[1,0]
	s_nop 0
	v_mul_f32_e32 v129, 0xbfb8aa3b, v178
	v_exp_f32_e32 v129, v129
	s_nop 0
	v_add_f32_e32 v129, 1.0, v129
	v_rcp_f32_e32 v182, v129
	v_mul_f32_e32 v129, 0xbfb8aa3b, v179
	v_exp_f32_e32 v129, v129
	s_nop 0
	v_add_f32_e32 v129, 1.0, v129
	v_rcp_f32_e32 v183, v129
	s_nop 0
	v_pk_mul_f32 v[178:179], v[178:179], v[182:183]
	v_pk_mul_f32 v[182:183], v[80:81], v[180:181] op_sel_hi:[1,0]
	s_nop 0
	v_mul_f32_e32 v129, 0xbfb8aa3b, v182
	v_exp_f32_e32 v129, v129
	s_nop 0
	v_add_f32_e32 v129, 1.0, v129
	v_rcp_f32_e32 v184, v129
	v_mul_f32_e32 v129, 0xbfb8aa3b, v183
	v_exp_f32_e32 v129, v129
	s_nop 0
	v_add_f32_e32 v129, 1.0, v129
	v_rcp_f32_e32 v185, v129
	s_nop 0
	v_pk_mul_f32 v[184:185], v[182:183], v[184:185]
	v_pk_mul_f32 v[182:183], v[82:83], v[180:181] op_sel_hi:[1,0]
	v_cvt_pk_bf16_f32 v184, v184, v185
	v_mul_f32_e32 v129, 0xbfb8aa3b, v182
	v_exp_f32_e32 v129, v129
	s_nop 0
	v_add_f32_e32 v129, 1.0, v129
; DI unsigned cvt_pk(float lo, float hi) { const f32x2 v = {lo, hi}; return __builtin_bit_cast(unsigned, __builtin_convertvector(v, bf16v2)); }
;     __device__ __forceinline__ void operator()(const f32x4 (&acc)[2][2][4][2], const Unit& u, int wr, int wc, int fr, int fq) const {
;     ...
;                 for (int m = 0; m < 4; ++m) {
;                     const int row = rowbase + ai * 128 + m * 16; const float r = ROW_RS(ai, m);
; #pragma unroll
;                     for (int bj = 0; bj < 2; ++bj) {
;                         float sv[8];
; #pragma unroll
;                         for (int n = 0; n < 2; ++n)
; #pragma unroll
;                             for (int j = 0; j < 4; ++j) { const float z = acc[ai][bj][m][n][j] * r; sv[4 * n + j] = z * __builtin_amdgcn_rcpf(1.0f + __builtin_amdgcn_exp2f(-1.44269504088896341f * z)); }
;                         u32x4 w; w.x = cvt_pk(sv[0], sv[1]); w.y = cvt_pk(sv[2], sv[3]); w.z = cvt_pk(sv[4], sv[5]); w.w = cvt_pk(sv[6], sv[7]);
;                         *(u32x4*)(zs + (size_t)row * DM + zcol + 32 * bj + 8 * fq) = w;
;                     }
	v_rcp_f32_e32 v186, v129
	v_mul_f32_e32 v129, 0xbfb8aa3b, v183
	v_exp_f32_e32 v129, v129
	s_nop 0
	v_add_f32_e32 v129, 1.0, v129
	v_rcp_f32_e32 v187, v129
	v_mul_f32_e32 v129, 0xbfb8aa3b, v134
	v_exp_f32_e32 v129, v129
	v_pk_mul_f32 v[186:187], v[182:183], v[186:187]
	v_cvt_pk_bf16_f32 v182, v138, v139
	v_cvt_pk_bf16_f32 v183, v178, v179
	v_cvt_pk_bf16_f32 v185, v186, v187
	v_add_f32_e32 v129, 1.0, v129
	global_store_dwordx4 v[136:137], v[182:185], off offset:64
	v_rcp_f32_e32 v136, v129
	v_mul_f32_e32 v129, 0xbfb8aa3b, v135
	v_exp_f32_e32 v129, v129
	s_nop 0
	v_add_f32_e32 v129, 1.0, v129
	v_rcp_f32_e32 v137, v129
	s_nop 0
	v_pk_mul_f32 v[134:135], v[134:135], v[136:137]
	v_pk_mul_f32 v[136:137], v[78:79], v[176:177] op_sel_hi:[1,0]
	v_cvt_pk_bf16_f32 v134, v134, v135
	v_mul_f32_e32 v129, 0xbfb8aa3b, v136
	v_exp_f32_e32 v129, v129
	s_nop 0
	v_add_f32_e32 v129, 1.0, v129
	v_rcp_f32_e32 v138, v129
	v_mul_f32_e32 v129, 0xbfb8aa3b, v137
	v_exp_f32_e32 v129, v129
	s_nop 0
	v_add_f32_e32 v129, 1.0, v129
	v_rcp_f32_e32 v139, v129
	s_nop 0
	v_pk_mul_f32 v[136:137], v[136:137], v[138:139]
	v_pk_mul_f32 v[138:139], v[68:69], v[176:177] op_sel_hi:[1,0]
	v_cvt_pk_bf16_f32 v135, v136, v137
	v_mul_f32_e32 v129, 0xbfb8aa3b, v138
	v_exp_f32_e32 v129, v129
	s_nop 0
	v_add_f32_e32 v129, 1.0, v129
	v_rcp_f32_e32 v178, v129
	v_mul_f32_e32 v129, 0xbfb8aa3b, v139
	v_exp_f32_e32 v129, v129
	s_nop 0
	v_add_f32_e32 v129, 1.0, v129
	v_rcp_f32_e32 v179, v129
	s_nop 0
	v_pk_mul_f32 v[138:139], v[138:139], v[178:179]
	v_pk_mul_f32 v[178:179], v[70:71], v[176:177] op_sel_hi:[1,0]
	v_cvt_pk_bf16_f32 v136, v138, v139
	v_mul_f32_e32 v129, 0xbfb8aa3b, v178
	v_exp_f32_e32 v129, v129
	s_nop 0
	v_add_f32_e32 v129, 1.0, v129
	v_rcp_f32_e32 v182, v129
	v_mul_f32_e32 v129, 0xbfb8aa3b, v179
	v_exp_f32_e32 v129, v129
	s_nop 0
	v_add_f32_e32 v129, 1.0, v129
	v_rcp_f32_e32 v183, v129
	s_nop 0
	v_pk_mul_f32 v[178:179], v[178:179], v[182:183]
	s_nop 0
	v_cvt_pk_bf16_f32 v137, v178, v179
	global_store_dwordx4 v[132:133], v[134:137], off
	s_nop 1
	v_pk_mul_f32 v[134:135], v[72:73], v[176:177] op_sel_hi:[1,0]
	s_nop 0
	v_mul_f32_e32 v129, 0xbfb8aa3b, v134
	v_exp_f32_e32 v129, v129
	s_nop 0
	v_add_f32_e32 v129, 1.0, v129
	v_rcp_f32_e32 v136, v129
	v_mul_f32_e32 v129, 0xbfb8aa3b, v135
	v_exp_f32_e32 v129, v129
	s_nop 0
	v_add_f32_e32 v129, 1.0, v129
	v_rcp_f32_e32 v137, v129
	s_nop 0
	v_pk_mul_f32 v[134:135], v[134:135], v[136:137]
	v_pk_mul_f32 v[136:137], v[74:75], v[176:177] op_sel_hi:[1,0]
	v_cvt_pk_bf16_f32 v134, v134, v135
	v_mul_f32_e32 v129, 0xbfb8aa3b, v136
	v_exp_f32_e32 v129, v129
	s_nop 0
	v_add_f32_e32 v129, 1.0, v129
	v_rcp_f32_e32 v138, v129
	v_mul_f32_e32 v129, 0xbfb8aa3b, v137
	v_exp_f32_e32 v129, v129
	s_nop 0
	v_add_f32_e32 v129, 1.0, v129
	v_rcp_f32_e32 v139, v129
	s_nop 0
	v_pk_mul_f32 v[136:137], v[136:137], v[138:139]
	v_pk_mul_f32 v[138:139], v[64:65], v[176:177] op_sel_hi:[1,0]
	v_cvt_pk_bf16_f32 v135, v136, v137
	v_mul_f32_e32 v129, 0xbfb8aa3b, v138
	v_exp_f32_e32 v129, v129
	s_nop 0
	v_add_f32_e32 v129, 1.0, v129
	v_rcp_f32_e32 v178, v129
	v_mul_f32_e32 v129, 0xbfb8aa3b, v139
	v_exp_f32_e32 v129, v129
	s_nop 0
	v_add_f32_e32 v129, 1.0, v129
	v_rcp_f32_e32 v179, v129
	s_nop 0
	v_pk_mul_f32 v[138:139], v[138:139], v[178:179]
	v_pk_mul_f32 v[178:179], v[66:67], v[176:177] op_sel_hi:[1,0]
	v_cvt_pk_bf16_f32 v136, v138, v139
	v_mul_f32_e32 v129, 0xbfb8aa3b, v178
	v_exp_f32_e32 v129, v129
	s_nop 0
	v_add_f32_e32 v129, 1.0, v129
	v_rcp_f32_e32 v182, v129
	v_mul_f32_e32 v129, 0xbfb8aa3b, v179
	v_exp_f32_e32 v129, v129
	s_nop 0
	v_add_f32_e32 v129, 1.0, v129
	v_rcp_f32_e32 v183, v129
	s_nop 0
	v_pk_mul_f32 v[178:179], v[178:179], v[182:183]
	s_nop 0
	v_cvt_pk_bf16_f32 v137, v178, v179
	global_store_dwordx4 v[132:133], v[134:137], off offset:64
	v_lshl_add_u64 v[132:133], v[130:131], 0, s[44:45]
	s_mov_b64 s[44:45], 0x48000
	v_pk_mul_f32 v[134:135], v[60:61], v[174:175] op_sel_hi:[1,0]
	s_nop 0
	v_mul_f32_e32 v129, 0xbfb8aa3b, v134
	v_exp_f32_e32 v129, v129
	s_nop 0
	v_add_f32_e32 v129, 1.0, v129
	v_rcp_f32_e32 v136, v129
	v_mul_f32_e32 v129, 0xbfb8aa3b, v135
	v_exp_f32_e32 v129, v129
	s_nop 0
	v_add_f32_e32 v129, 1.0, v129
	v_rcp_f32_e32 v137, v129
	s_nop 0
	v_pk_mul_f32 v[134:135], v[134:135], v[136:137]
	v_pk_mul_f32 v[136:137], v[62:63], v[174:175] op_sel_hi:[1,0]
	v_cvt_pk_bf16_f32 v134, v134, v135
	v_mul_f32_e32 v129, 0xbfb8aa3b, v136
	v_exp_f32_e32 v129, v129
	s_nop 0
	v_add_f32_e32 v129, 1.0, v129
	v_rcp_f32_e32 v138, v129
	v_mul_f32_e32 v129, 0xbfb8aa3b, v137
	v_exp_f32_e32 v129, v129
	s_nop 0
	v_add_f32_e32 v129, 1.0, v129
	v_rcp_f32_e32 v139, v129
	s_nop 0
	v_pk_mul_f32 v[136:137], v[136:137], v[138:139]
	v_pk_mul_f32 v[138:139], v[52:53], v[174:175] op_sel_hi:[1,0]
	v_cvt_pk_bf16_f32 v135, v136, v137
	v_mul_f32_e32 v129, 0xbfb8aa3b, v138
	v_exp_f32_e32 v129, v129
	s_nop 0
	v_add_f32_e32 v129, 1.0, v129
	v_rcp_f32_e32 v178, v129
	v_mul_f32_e32 v129, 0xbfb8aa3b, v139
	v_exp_f32_e32 v129, v129
	s_nop 0
	v_add_f32_e32 v129, 1.0, v129
	v_rcp_f32_e32 v179, v129
	s_nop 0
	v_pk_mul_f32 v[138:139], v[138:139], v[178:179]
	v_pk_mul_f32 v[178:179], v[54:55], v[174:175] op_sel_hi:[1,0]
	v_cvt_pk_bf16_f32 v136, v138, v139
	v_mul_f32_e32 v129, 0xbfb8aa3b, v178
	v_exp_f32_e32 v129, v129
	v_add_co_u32_e32 v138, vcc, s2, v130
	s_mov_b32 s2, 0x48000
	v_add_f32_e32 v129, 1.0, v129
	v_rcp_f32_e32 v182, v129
	v_mul_f32_e32 v129, 0xbfb8aa3b, v179
	v_exp_f32_e32 v129, v129
	v_addc_co_u32_e32 v139, vcc, 0, v131, vcc
	v_add_f32_e32 v129, 1.0, v129
	v_rcp_f32_e32 v183, v129
	s_nop 0
	v_pk_mul_f32 v[178:179], v[178:179], v[182:183]
	s_nop 0
	v_cvt_pk_bf16_f32 v137, v178, v179
; DI unsigned cvt_pk(float lo, float hi) { const f32x2 v = {lo, hi}; return __builtin_bit_cast(unsigned, __builtin_convertvector(v, bf16v2)); }
;     __device__ __forceinline__ void operator()(const f32x4 (&acc)[2][2][4][2], const Unit& u, int wr, int wc, int fr, int fq) const {
;     ...
; #pragma unroll
;             for (int ai = 0; ai < 2; ++ai)
; #pragma unroll
;                 for (int m = 0; m < 4; ++m) {
;                     const int row = rowbase + ai * 128 + m * 16; const float r = ROW_RS(ai, m);
; #pragma unroll
;                     for (int bj = 0; bj < 2; ++bj) {
;                         float sv[8];
; #pragma unroll
;                         for (int n = 0; n < 2; ++n)
; #pragma unroll
;                             for (int j = 0; j < 4; ++j) { const float z = acc[ai][bj][m][n][j] * r; sv[4 * n + j] = z * __builtin_amdgcn_rcpf(1.0f + __builtin_amdgcn_exp2f(-1.44269504088896341f * z)); }
;                         u32x4 w; w.x = cvt_pk(sv[0], sv[1]); w.y = cvt_pk(sv[2], sv[3]); w.z = cvt_pk(sv[4], sv[5]); w.w = cvt_pk(sv[6], sv[7]);
;                         *(u32x4*)(zs + (size_t)row * DM + zcol + 32 * bj + 8 * fq) = w;
;                     }
	global_store_dwordx4 v[138:139], v[134:137], off
	s_nop 1
	v_pk_mul_f32 v[134:135], v[56:57], v[174:175] op_sel_hi:[1,0]
	s_nop 0
	v_mul_f32_e32 v129, 0xbfb8aa3b, v134
	v_exp_f32_e32 v129, v129
	s_nop 0
	v_add_f32_e32 v129, 1.0, v129
	v_rcp_f32_e32 v136, v129
	v_mul_f32_e32 v129, 0xbfb8aa3b, v135
	v_exp_f32_e32 v129, v129
	s_nop 0
	v_add_f32_e32 v129, 1.0, v129
	v_rcp_f32_e32 v137, v129
	s_nop 0
	v_pk_mul_f32 v[134:135], v[134:135], v[136:137]
	v_pk_mul_f32 v[136:137], v[58:59], v[174:175] op_sel_hi:[1,0]
	v_cvt_pk_bf16_f32 v134, v134, v135
	v_mul_f32_e32 v129, 0xbfb8aa3b, v136
	v_exp_f32_e32 v129, v129
	s_nop 0
	v_add_f32_e32 v129, 1.0, v129
	v_rcp_f32_e32 v138, v129
	v_mul_f32_e32 v129, 0xbfb8aa3b, v137
	v_exp_f32_e32 v129, v129
	s_nop 0
	v_add_f32_e32 v129, 1.0, v129
	v_rcp_f32_e32 v139, v129
	s_nop 0
	v_pk_mul_f32 v[136:137], v[136:137], v[138:139]
	v_pk_mul_f32 v[138:139], v[48:49], v[174:175] op_sel_hi:[1,0]
	v_cvt_pk_bf16_f32 v135, v136, v137
	v_mul_f32_e32 v129, 0xbfb8aa3b, v138
	v_exp_f32_e32 v129, v129
	s_nop 0
	v_add_f32_e32 v129, 1.0, v129
	v_rcp_f32_e32 v178, v129
	v_mul_f32_e32 v129, 0xbfb8aa3b, v139
	v_exp_f32_e32 v129, v129
	s_nop 0
	v_add_f32_e32 v129, 1.0, v129
	v_rcp_f32_e32 v179, v129
	s_nop 0
	v_pk_mul_f32 v[138:139], v[138:139], v[178:179]
	v_pk_mul_f32 v[178:179], v[50:51], v[174:175] op_sel_hi:[1,0]
	v_cvt_pk_bf16_f32 v136, v138, v139
	v_mul_f32_e32 v129, 0xbfb8aa3b, v178
	v_exp_f32_e32 v129, v129
	s_nop 0
	v_add_f32_e32 v129, 1.0, v129
	v_rcp_f32_e32 v182, v129
	v_mul_f32_e32 v129, 0xbfb8aa3b, v179
	v_exp_f32_e32 v129, v129
	s_nop 0
	v_add_f32_e32 v129, 1.0, v129
	v_rcp_f32_e32 v183, v129
	s_nop 0
	v_pk_mul_f32 v[178:179], v[178:179], v[182:183]
	s_nop 0
	v_cvt_pk_bf16_f32 v137, v178, v179
	global_store_dwordx4 v[132:133], v[134:137], off offset:64
	v_lshl_add_u64 v[132:133], v[130:131], 0, s[44:45]
	s_mov_b64 s[44:45], 0x50000
	v_pk_mul_f32 v[134:135], v[44:45], v[172:173] op_sel_hi:[1,0]
	s_nop 0
	v_mul_f32_e32 v129, 0xbfb8aa3b, v134
	v_exp_f32_e32 v129, v129
	s_nop 0
	v_add_f32_e32 v129, 1.0, v129
	v_rcp_f32_e32 v136, v129
	v_mul_f32_e32 v129, 0xbfb8aa3b, v135
	v_exp_f32_e32 v129, v129
	s_nop 0
	v_add_f32_e32 v129, 1.0, v129
	v_rcp_f32_e32 v137, v129
	s_nop 0
	v_pk_mul_f32 v[134:135], v[134:135], v[136:137]
	v_pk_mul_f32 v[136:137], v[46:47], v[172:173] op_sel_hi:[1,0]
	v_cvt_pk_bf16_f32 v134, v134, v135
	v_mul_f32_e32 v129, 0xbfb8aa3b, v136
	v_exp_f32_e32 v129, v129
	s_nop 0
	v_add_f32_e32 v129, 1.0, v129
	v_rcp_f32_e32 v138, v129
	v_mul_f32_e32 v129, 0xbfb8aa3b, v137
	v_exp_f32_e32 v129, v129
	s_nop 0
	v_add_f32_e32 v129, 1.0, v129
	v_rcp_f32_e32 v139, v129
	s_nop 0
	v_pk_mul_f32 v[136:137], v[136:137], v[138:139]
	v_pk_mul_f32 v[138:139], v[36:37], v[172:173] op_sel_hi:[1,0]
	v_cvt_pk_bf16_f32 v135, v136, v137
	v_mul_f32_e32 v129, 0xbfb8aa3b, v138
	v_exp_f32_e32 v129, v129
	s_nop 0
	v_add_f32_e32 v129, 1.0, v129
	v_rcp_f32_e32 v178, v129
	v_mul_f32_e32 v129, 0xbfb8aa3b, v139
	v_exp_f32_e32 v129, v129
	s_nop 0
	v_add_f32_e32 v129, 1.0, v129
	v_rcp_f32_e32 v179, v129
	s_nop 0
	v_pk_mul_f32 v[138:139], v[138:139], v[178:179]
	v_pk_mul_f32 v[178:179], v[38:39], v[172:173] op_sel_hi:[1,0]
	v_cvt_pk_bf16_f32 v136, v138, v139
	v_mul_f32_e32 v129, 0xbfb8aa3b, v178
	v_exp_f32_e32 v129, v129
	v_add_co_u32_e32 v138, vcc, s2, v130
	s_mov_b32 s2, 0x50000
	v_add_f32_e32 v129, 1.0, v129
	v_rcp_f32_e32 v182, v129
	v_mul_f32_e32 v129, 0xbfb8aa3b, v179
	v_exp_f32_e32 v129, v129
	v_addc_co_u32_e32 v139, vcc, 0, v131, vcc
	v_add_f32_e32 v129, 1.0, v129
	v_rcp_f32_e32 v183, v129
	s_nop 0
	v_pk_mul_f32 v[178:179], v[178:179], v[182:183]
	s_nop 0
	v_cvt_pk_bf16_f32 v137, v178, v179
	global_store_dwordx4 v[138:139], v[134:137], off
	s_nop 1
	v_pk_mul_f32 v[134:135], v[40:41], v[172:173] op_sel_hi:[1,0]
	s_nop 0
	v_mul_f32_e32 v129, 0xbfb8aa3b, v134
	v_exp_f32_e32 v129, v129
	s_nop 0
	v_add_f32_e32 v129, 1.0, v129
	v_rcp_f32_e32 v136, v129
	v_mul_f32_e32 v129, 0xbfb8aa3b, v135
	v_exp_f32_e32 v129, v129
	s_nop 0
	v_add_f32_e32 v129, 1.0, v129
	v_rcp_f32_e32 v137, v129
	s_nop 0
	v_pk_mul_f32 v[134:135], v[134:135], v[136:137]
	v_pk_mul_f32 v[136:137], v[42:43], v[172:173] op_sel_hi:[1,0]
	v_cvt_pk_bf16_f32 v134, v134, v135
	v_mul_f32_e32 v129, 0xbfb8aa3b, v136
	v_exp_f32_e32 v129, v129
	s_nop 0
	v_add_f32_e32 v129, 1.0, v129
	v_rcp_f32_e32 v138, v129
	v_mul_f32_e32 v129, 0xbfb8aa3b, v137
	v_exp_f32_e32 v129, v129
	s_nop 0
	v_add_f32_e32 v129, 1.0, v129
	v_rcp_f32_e32 v139, v129
	s_nop 0
	v_pk_mul_f32 v[136:137], v[136:137], v[138:139]
	v_pk_mul_f32 v[138:139], v[32:33], v[172:173] op_sel_hi:[1,0]
	v_cvt_pk_bf16_f32 v135, v136, v137
	v_mul_f32_e32 v129, 0xbfb8aa3b, v138
	v_exp_f32_e32 v129, v129
	s_nop 0
	v_add_f32_e32 v129, 1.0, v129
	v_rcp_f32_e32 v178, v129
	v_mul_f32_e32 v129, 0xbfb8aa3b, v139
	v_exp_f32_e32 v129, v129
	s_nop 0
	v_add_f32_e32 v129, 1.0, v129
	v_rcp_f32_e32 v179, v129
	s_nop 0
	v_pk_mul_f32 v[138:139], v[138:139], v[178:179]
	v_pk_mul_f32 v[178:179], v[34:35], v[172:173] op_sel_hi:[1,0]
	v_cvt_pk_bf16_f32 v136, v138, v139
	v_mul_f32_e32 v129, 0xbfb8aa3b, v178
	v_exp_f32_e32 v129, v129
	s_nop 0
	v_add_f32_e32 v129, 1.0, v129
	v_rcp_f32_e32 v182, v129
	v_mul_f32_e32 v129, 0xbfb8aa3b, v179
	v_exp_f32_e32 v129, v129
	s_nop 0
	v_add_f32_e32 v129, 1.0, v129
	v_rcp_f32_e32 v183, v129
	s_nop 0
	v_pk_mul_f32 v[178:179], v[178:179], v[182:183]
	s_nop 0
	v_cvt_pk_bf16_f32 v137, v178, v179
	global_store_dwordx4 v[132:133], v[134:137], off offset:64
	v_lshl_add_u64 v[132:133], v[130:131], 0, s[44:45]
	s_mov_b64 s[44:45], 0x58000
	v_pk_mul_f32 v[134:135], v[28:29], v[170:171] op_sel_hi:[1,0]
	s_nop 0
	v_mul_f32_e32 v129, 0xbfb8aa3b, v134
; DI unsigned cvt_pk(float lo, float hi) { const f32x2 v = {lo, hi}; return __builtin_bit_cast(unsigned, __builtin_convertvector(v, bf16v2)); }
;     __device__ __forceinline__ void operator()(const f32x4 (&acc)[2][2][4][2], const Unit& u, int wr, int wc, int fr, int fq) const {
;     ...
; #pragma unroll
;             for (int ai = 0; ai < 2; ++ai)
; #pragma unroll
;                 for (int m = 0; m < 4; ++m) {
;                     const int row = rowbase + ai * 128 + m * 16; const float r = ROW_RS(ai, m);
; #pragma unroll
;                     for (int bj = 0; bj < 2; ++bj) {
;                         float sv[8];
; #pragma unroll
;                         for (int n = 0; n < 2; ++n)
; #pragma unroll
;                             for (int j = 0; j < 4; ++j) { const float z = acc[ai][bj][m][n][j] * r; sv[4 * n + j] = z * __builtin_amdgcn_rcpf(1.0f + __builtin_amdgcn_exp2f(-1.44269504088896341f * z)); }
;                         u32x4 w; w.x = cvt_pk(sv[0], sv[1]); w.y = cvt_pk(sv[2], sv[3]); w.z = cvt_pk(sv[4], sv[5]); w.w = cvt_pk(sv[6], sv[7]);
;                         *(u32x4*)(zs + (size_t)row * DM + zcol + 32 * bj + 8 * fq) = w;
;                     }
	v_exp_f32_e32 v129, v129
	s_nop 0
	v_add_f32_e32 v129, 1.0, v129
	v_rcp_f32_e32 v136, v129
	v_mul_f32_e32 v129, 0xbfb8aa3b, v135
	v_exp_f32_e32 v129, v129
	s_nop 0
	v_add_f32_e32 v129, 1.0, v129
	v_rcp_f32_e32 v137, v129
	s_nop 0
	v_pk_mul_f32 v[134:135], v[134:135], v[136:137]
	v_pk_mul_f32 v[136:137], v[30:31], v[170:171] op_sel_hi:[1,0]
	v_cvt_pk_bf16_f32 v134, v134, v135
	v_mul_f32_e32 v129, 0xbfb8aa3b, v136
	v_exp_f32_e32 v129, v129
	s_nop 0
	v_add_f32_e32 v129, 1.0, v129
	v_rcp_f32_e32 v138, v129
	v_mul_f32_e32 v129, 0xbfb8aa3b, v137
	v_exp_f32_e32 v129, v129
	s_nop 0
	v_add_f32_e32 v129, 1.0, v129
	v_rcp_f32_e32 v139, v129
	s_nop 0
	v_pk_mul_f32 v[136:137], v[136:137], v[138:139]
	v_pk_mul_f32 v[138:139], v[20:21], v[170:171] op_sel_hi:[1,0]
	v_cvt_pk_bf16_f32 v135, v136, v137
	v_mul_f32_e32 v129, 0xbfb8aa3b, v138
	v_exp_f32_e32 v129, v129
	s_nop 0
	v_add_f32_e32 v129, 1.0, v129
	v_rcp_f32_e32 v178, v129
	v_mul_f32_e32 v129, 0xbfb8aa3b, v139
	v_exp_f32_e32 v129, v129
	s_nop 0
	v_add_f32_e32 v129, 1.0, v129
	v_rcp_f32_e32 v179, v129
	s_nop 0
	v_pk_mul_f32 v[138:139], v[138:139], v[178:179]
	v_pk_mul_f32 v[178:179], v[22:23], v[170:171] op_sel_hi:[1,0]
	v_cvt_pk_bf16_f32 v136, v138, v139
	v_mul_f32_e32 v129, 0xbfb8aa3b, v178
	v_exp_f32_e32 v129, v129
	v_add_co_u32_e32 v138, vcc, s2, v130
	s_mov_b32 s2, 0x58000
	v_add_f32_e32 v129, 1.0, v129
	v_rcp_f32_e32 v182, v129
	v_mul_f32_e32 v129, 0xbfb8aa3b, v179
	v_exp_f32_e32 v129, v129
	v_addc_co_u32_e32 v139, vcc, 0, v131, vcc
	v_add_f32_e32 v129, 1.0, v129
	v_rcp_f32_e32 v183, v129
	s_nop 0
	v_pk_mul_f32 v[178:179], v[178:179], v[182:183]
	s_nop 0
	v_cvt_pk_bf16_f32 v137, v178, v179
	global_store_dwordx4 v[138:139], v[134:137], off
	s_nop 1
	v_pk_mul_f32 v[134:135], v[24:25], v[170:171] op_sel_hi:[1,0]
	s_nop 0
	v_mul_f32_e32 v129, 0xbfb8aa3b, v134
	v_exp_f32_e32 v129, v129
	s_nop 0
	v_add_f32_e32 v129, 1.0, v129
	v_rcp_f32_e32 v136, v129
	v_mul_f32_e32 v129, 0xbfb8aa3b, v135
	v_exp_f32_e32 v129, v129
	s_nop 0
	v_add_f32_e32 v129, 1.0, v129
	v_rcp_f32_e32 v137, v129
	s_nop 0
	v_pk_mul_f32 v[134:135], v[134:135], v[136:137]
	v_pk_mul_f32 v[136:137], v[26:27], v[170:171] op_sel_hi:[1,0]
	v_cvt_pk_bf16_f32 v134, v134, v135
	v_mul_f32_e32 v129, 0xbfb8aa3b, v136
	v_exp_f32_e32 v129, v129
	s_nop 0
	v_add_f32_e32 v129, 1.0, v129
	v_rcp_f32_e32 v138, v129
	v_mul_f32_e32 v129, 0xbfb8aa3b, v137
	v_exp_f32_e32 v129, v129
	s_nop 0
	v_add_f32_e32 v129, 1.0, v129
	v_rcp_f32_e32 v139, v129
	s_nop 0
	v_pk_mul_f32 v[136:137], v[136:137], v[138:139]
	v_pk_mul_f32 v[138:139], v[16:17], v[170:171] op_sel_hi:[1,0]
	v_cvt_pk_bf16_f32 v135, v136, v137
	v_mul_f32_e32 v129, 0xbfb8aa3b, v138
	v_exp_f32_e32 v129, v129
	s_nop 0
	v_add_f32_e32 v129, 1.0, v129
	v_rcp_f32_e32 v178, v129
	v_mul_f32_e32 v129, 0xbfb8aa3b, v139
	v_exp_f32_e32 v129, v129
	s_nop 0
	v_add_f32_e32 v129, 1.0, v129
	v_rcp_f32_e32 v179, v129
	s_nop 0
	v_pk_mul_f32 v[138:139], v[138:139], v[178:179]
	v_pk_mul_f32 v[178:179], v[18:19], v[170:171] op_sel_hi:[1,0]
	v_cvt_pk_bf16_f32 v136, v138, v139
	v_mul_f32_e32 v129, 0xbfb8aa3b, v178
	v_exp_f32_e32 v129, v129
	s_nop 0
	v_add_f32_e32 v129, 1.0, v129
	v_rcp_f32_e32 v182, v129
	v_mul_f32_e32 v129, 0xbfb8aa3b, v179
	v_exp_f32_e32 v129, v129
	s_nop 0
	v_add_f32_e32 v129, 1.0, v129
	v_rcp_f32_e32 v183, v129
	s_nop 0
	v_pk_mul_f32 v[178:179], v[178:179], v[182:183]
	s_nop 0
	v_cvt_pk_bf16_f32 v137, v178, v179
	global_store_dwordx4 v[132:133], v[134:137], off offset:64
	v_lshl_add_u64 v[132:133], v[130:131], 0, s[44:45]
	v_add_co_u32_e32 v130, vcc, s2, v130
; DI unsigned cvt_pk(float lo, float hi) { const f32x2 v = {lo, hi}; return __builtin_bit_cast(unsigned, __builtin_convertvector(v, bf16v2)); }
;     __device__ __forceinline__ void operator()(const f32x4 (&acc)[2][2][4][2], const Unit& u, int wr, int wc, int fr, int fq) const {
;     ...
; #pragma unroll
;             for (int ai = 0; ai < 2; ++ai)
; #pragma unroll
;                 for (int m = 0; m < 4; ++m) {
;                     const int row = rowbase + ai * 128 + m * 16; const float r = ROW_RS(ai, m);
; #pragma unroll
;                     for (int bj = 0; bj < 2; ++bj) {
;                         float sv[8];
; #pragma unroll
;                         for (int n = 0; n < 2; ++n)
; #pragma unroll
;                             for (int j = 0; j < 4; ++j) { const float z = acc[ai][bj][m][n][j] * r; sv[4 * n + j] = z * __builtin_amdgcn_rcpf(1.0f + __builtin_amdgcn_exp2f(-1.44269504088896341f * z)); }
;                         u32x4 w; w.x = cvt_pk(sv[0], sv[1]); w.y = cvt_pk(sv[2], sv[3]); w.z = cvt_pk(sv[4], sv[5]); w.w = cvt_pk(sv[6], sv[7]);
;                         *(u32x4*)(zs + (size_t)row * DM + zcol + 32 * bj + 8 * fq) = w;
;                     }
	v_pk_mul_f32 v[134:135], v[12:13], v[166:167] op_sel_hi:[1,0]
	s_nop 0
	v_addc_co_u32_e32 v131, vcc, 0, v131, vcc
	v_mul_f32_e32 v129, 0xbfb8aa3b, v134
	v_exp_f32_e32 v129, v129
	s_nop 0
	v_add_f32_e32 v129, 1.0, v129
	v_rcp_f32_e32 v136, v129
	v_mul_f32_e32 v129, 0xbfb8aa3b, v135
	v_exp_f32_e32 v129, v129
	s_nop 0
	v_add_f32_e32 v129, 1.0, v129
	v_rcp_f32_e32 v137, v129
	s_nop 0
	v_pk_mul_f32 v[134:135], v[134:135], v[136:137]
	v_pk_mul_f32 v[136:137], v[14:15], v[166:167] op_sel_hi:[1,0]
	v_cvt_pk_bf16_f32 v134, v134, v135
	v_mul_f32_e32 v129, 0xbfb8aa3b, v136
	v_exp_f32_e32 v129, v129
	s_nop 0
	v_add_f32_e32 v129, 1.0, v129
	v_rcp_f32_e32 v138, v129
	v_mul_f32_e32 v129, 0xbfb8aa3b, v137
	v_exp_f32_e32 v129, v129
	s_nop 0
	v_add_f32_e32 v129, 1.0, v129
	v_rcp_f32_e32 v139, v129
	s_nop 0
	v_pk_mul_f32 v[136:137], v[136:137], v[138:139]
	v_pk_mul_f32 v[138:139], v[4:5], v[166:167] op_sel_hi:[1,0]
	v_cvt_pk_bf16_f32 v135, v136, v137
	v_mul_f32_e32 v129, 0xbfb8aa3b, v138
	v_exp_f32_e32 v129, v129
	s_nop 0
	v_add_f32_e32 v129, 1.0, v129
	v_rcp_f32_e32 v178, v129
	v_mul_f32_e32 v129, 0xbfb8aa3b, v139
	v_exp_f32_e32 v129, v129
	s_nop 0
	v_add_f32_e32 v129, 1.0, v129
	v_rcp_f32_e32 v179, v129
	s_nop 0
	v_pk_mul_f32 v[138:139], v[138:139], v[178:179]
	v_pk_mul_f32 v[178:179], v[6:7], v[166:167] op_sel_hi:[1,0]
	v_cvt_pk_bf16_f32 v136, v138, v139
	v_mul_f32_e32 v129, 0xbfb8aa3b, v178
	v_exp_f32_e32 v129, v129
	s_nop 0
	v_add_f32_e32 v129, 1.0, v129
	v_rcp_f32_e32 v182, v129
	v_mul_f32_e32 v129, 0xbfb8aa3b, v179
	v_exp_f32_e32 v129, v129
	s_nop 0
	v_add_f32_e32 v129, 1.0, v129
	v_rcp_f32_e32 v183, v129
	s_nop 0
	v_pk_mul_f32 v[178:179], v[178:179], v[182:183]
	s_nop 0
	v_cvt_pk_bf16_f32 v137, v178, v179
	global_store_dwordx4 v[130:131], v[134:137], off
	v_pk_mul_f32 v[130:131], v[8:9], v[166:167] op_sel_hi:[1,0]
	s_nop 0
	v_mul_f32_e32 v129, 0xbfb8aa3b, v130
	v_exp_f32_e32 v129, v129
	s_nop 0
	v_add_f32_e32 v129, 1.0, v129
	v_rcp_f32_e32 v134, v129
	v_mul_f32_e32 v129, 0xbfb8aa3b, v131
	v_exp_f32_e32 v129, v129
	s_nop 0
	v_add_f32_e32 v129, 1.0, v129
	v_rcp_f32_e32 v135, v129
	s_nop 0
	v_pk_mul_f32 v[130:131], v[130:131], v[134:135]
	v_pk_mul_f32 v[134:135], v[10:11], v[166:167] op_sel_hi:[1,0]
	s_nop 0
	v_mul_f32_e32 v129, 0xbfb8aa3b, v134
	v_exp_f32_e32 v129, v129
	s_nop 0
	v_add_f32_e32 v129, 1.0, v129
	v_rcp_f32_e32 v136, v129
	v_mul_f32_e32 v129, 0xbfb8aa3b, v135
	v_exp_f32_e32 v129, v129
	s_nop 0
	v_add_f32_e32 v129, 1.0, v129
	v_rcp_f32_e32 v137, v129
	s_nop 0
	v_pk_mul_f32 v[136:137], v[134:135], v[136:137]
	v_pk_mul_f32 v[134:135], v[0:1], v[166:167] op_sel_hi:[1,0]
	s_nop 0
	v_mul_f32_e32 v129, 0xbfb8aa3b, v134
	v_exp_f32_e32 v129, v129
	s_nop 0
	v_add_f32_e32 v129, 1.0, v129
	v_rcp_f32_e32 v138, v129
	v_mul_f32_e32 v129, 0xbfb8aa3b, v135
	v_exp_f32_e32 v129, v129
	s_nop 0
	v_add_f32_e32 v129, 1.0, v129
	v_rcp_f32_e32 v139, v129
	s_nop 0
	v_pk_mul_f32 v[138:139], v[134:135], v[138:139]
	v_pk_mul_f32 v[134:135], v[2:3], v[166:167] op_sel_hi:[1,0]
	s_nop 0
	v_mul_f32_e32 v129, 0xbfb8aa3b, v134
	v_exp_f32_e32 v129, v129
	s_nop 0
	v_add_f32_e32 v129, 1.0, v129
	v_rcp_f32_e32 v178, v129
	v_mul_f32_e32 v129, 0xbfb8aa3b, v135
	v_exp_f32_e32 v129, v129
	s_nop 0
	v_add_f32_e32 v129, 1.0, v129
	v_rcp_f32_e32 v179, v129
	s_nop 0
	v_pk_mul_f32 v[178:179], v[134:135], v[178:179]
	v_cvt_pk_bf16_f32 v134, v130, v131
	v_cvt_pk_bf16_f32 v135, v136, v137
	v_cvt_pk_bf16_f32 v136, v138, v139
	v_cvt_pk_bf16_f32 v137, v178, v179
	global_store_dwordx4 v[132:133], v[134:137], off offset:64
